# past/own: one static s_setprio 1 for waves 4-7 over the phase (lever 7.4)
# baseline (speedup 1.0000x reference)
.LBB0_248:
	s_or_b64 exec, exec, s[0:1]
	s_waitcnt vmcnt(4)
	v_cndmask_b32_e64 v0, 0, 1, s[40:41]
	s_andn2_b64 vcc, exec, s[40:41]
	v_readlane_b32 s36, v254, 57
	v_cmp_ne_u32_e64 s[6:7], 1, v0
	v_lshlrev_b32_e32 v112, 6, v194
	v_lshlrev_b32_e32 v108, 6, v123
	v_lshrrev_b32_e32 v109, 5, v147
	v_lshlrev_b32_e32 v110, 6, v182
	v_lshrrev_b32_e32 v111, 5, v190
	v_lshlrev_b32_e32 v114, 6, v183
	v_lshrrev_b32_e32 v113, 5, v180
	v_cmp_eq_u32_e64 s[8:9], 0, v181
	v_readlane_b32 s37, v254, 58
	v_readlane_b32 s38, v254, 59
	v_readlane_b32 s39, v254, 60
	v_readlane_b32 s42, v254, 63
	v_readlane_b32 s43, v255, 0
	v_readlane_b32 s44, v255, 1
	v_readlane_b32 s45, v255, 2
	v_readlane_b32 s46, v255, 3
	v_readlane_b32 s47, v255, 4
	v_readlane_b32 s48, v255, 5
	v_readlane_b32 s49, v255, 6
	v_readlane_b32 s50, v255, 7
	v_readlane_b32 s51, v255, 8
	s_barrier
	v_readlane_b32 s40, v254, 61
	v_readlane_b32 s41, v254, 62
	s_cbranch_vccnz .LBB0_266
	v_and_b32_e32 v116, 0x70, v128
	v_and_b32_e32 v0, 0x1f0, v128
	v_add_u32_e32 v1, 0, v116
	v_add_u32_e32 v3, 0, v0
	s_movk_i32 s0, 0x90
	s_mov_b32 s4, 0x9000
	s_waitcnt vmcnt(0)
	v_mul_u32_u24_e32 v5, 0x210, v109
	v_mov_b32_e32 v117, 0
	v_mad_u32_u24 v115, v194, s0, v1
	v_mad_u32_u24 v169, v123, s0, v1
	v_add3_u32 v170, v3, v5, s4
	v_mad_u32_u24 v171, v182, s0, v1
	v_mul_u32_u24_e32 v5, 0x210, v111
	v_mad_u32_u24 v173, v183, s0, v1
	v_mul_u32_u24_e32 v1, 0x210, v113
	v_mul_u32_u24_e32 v4, 0x210, v197
	v_add3_u32 v172, v3, v5, s4
	v_add3_u32 v174, v3, v1, s4
	v_mul_u32_u24_e32 v5, 0x210, v146
	v_mov_b32_e32 v1, v117
	v_lshlrev_b32_e32 v2, 12, v197
	v_add3_u32 v168, v3, v4, s4
	v_lshlrev_b32_e32 v4, 12, v109
	v_lshlrev_b32_e32 v6, 12, v111
	v_lshlrev_b32_e32 v8, 12, v113
	v_lshl_or_b32 v175, v196, 5, v146
	v_mov_b32_e32 v121, v117
	v_mul_u32_u24_e32 v3, 0x90, v146
	v_lshl_add_u64 v[126:127], s[68:69], 0, v[0:1]
	v_mov_b32_e32 v125, v117
	v_add3_u32 v0, v5, v120, 0
	s_mov_b32 s1, 0
	v_or_b32_e32 v176, 16, v175
	v_cmp_eq_u32_e64 s[10:11], 0, v184
	v_cmp_gt_u32_e64 s[12:13], 2, v181
	v_lshl_add_u64 v[118:119], s[66:67], 0, v[116:117]
	v_lshl_add_u64 v[128:129], s[64:65], 0, v[124:125]
	v_lshl_add_u64 v[130:131], s[50:51], 0, v[120:121]
	v_add_u32_e32 v121, 0x9000, v0
	v_add3_u32 v125, v3, v124, 0
	v_lshlrev_b32_e32 v132, 1, v112
	v_lshlrev_b32_e32 v134, 1, v2
	v_lshlrev_b32_e32 v136, 1, v108
	v_lshlrev_b32_e32 v138, 1, v4
	v_lshlrev_b32_e32 v140, 1, v110
	v_lshlrev_b32_e32 v142, 1, v6
	v_lshlrev_b32_e32 v148, 1, v114
	v_lshlrev_b32_e32 v150, 1, v8
	s_mov_b32 s4, 0xf149f2ca
	s_mov_b32 s5, s2
	v_readfirstlane_b32 s90, v196
	s_nop 3
	s_cmp_ge_u32 s90, 4
	s_cbranch_scc0 .Lpast_prio_done
	s_setprio 1
.Lpast_prio_done:
	s_branch .LBB0_251
.LBB0_250:
	s_add_i32 s5, s5, s3
	s_cmpk_gt_i32 s5, 0xff
	s_cbranch_scc1 .LBB0_266

.LBB0_266:
	s_setprio 0
	s_waitcnt vmcnt(0) lgkmcnt(0)
	s_barrier
	s_mov_b64 s[0:1], exec
	v_readlane_b32 s4, v254, 7
	v_readlane_b32 s5, v254, 8
	s_and_b64 s[4:5], s[0:1], s[4:5]
	s_mov_b64 exec, s[4:5]
	s_cbranch_execz .LBB0_275
	s_mov_b64 s[10:11], exec
	s_waitcnt vmcnt(3)
	v_mbcnt_lo_u32_b32 v0, s10, 0
	v_mbcnt_hi_u32_b32 v0, s11, v0
	v_cmp_eq_u32_e32 vcc, 0, v0
	s_and_saveexec_b64 s[8:9], vcc
	s_cbranch_execz .LBB0_269
	v_readlane_b32 s4, v254, 6
	s_lshl_b32 s4, s4, 8
	s_add_u32 s4, s44, s4
	s_addc_u32 s5, s45, 0
	s_bcnt1_i32_b64 s10, s[10:11]
	v_mov_b32_e32 v1, 0x1000
	v_mov_b32_e32 v2, s10
	global_atomic_add v1, v1, v2, s[4:5] offset:256 sc0

.LBB0_275:
	s_or_b64 exec, exec, s[0:1]
	s_and_b64 vcc, exec, s[82:83]
	s_barrier
	s_cbranch_vccnz .LBB0_298
	s_waitcnt vmcnt(3)
	v_lshlrev_b32_e32 v1, 3, v188
	v_and_b32_e32 v0, 56, v1
	s_waitcnt vmcnt(0)
	v_and_b32_e32 v4, 0xf8, v1
	v_mul_u32_u24_e32 v1, 0x90, v194
	v_lshlrev_b32_e32 v3, 1, v0
	v_add3_u32 v175, 0, v1, v3
	v_mul_u32_u24_e32 v1, 0x90, v123
	v_add3_u32 v123, 0, v1, v3
	v_mul_u32_u24_e32 v1, 0x90, v182
	v_add3_u32 v176, 0, v1, v3
	v_mul_u32_u24_e32 v1, 0x90, v183
	v_add3_u32 v177, 0, v1, v3
	v_mul_u32_u24_e32 v1, 0x210, v197
	v_lshlrev_b32_e32 v3, 1, v4
	v_add3_u32 v182, 0, v1, v3
	v_mul_u32_u24_e32 v1, 0x210, v109
	v_add3_u32 v183, 0, v1, v3
	v_mul_u32_u24_e32 v1, 0x210, v111
	v_mov_b32_e32 v121, 0
	v_add3_u32 v185, 0, v1, v3
	v_mul_u32_u24_e32 v1, 0x210, v113
	v_and_b32_e32 v252, 4, v196
	v_lshrrev_b32_e32 v252, 1, v252
	v_xor_b32_e32 v252, v196, v252
	v_lshlrev_b32_e32 v174, 5, v252
	v_add3_u32 v186, 0, v1, v3
	v_mul_u32_u24_e32 v1, 0x90, v146
	v_mul_u32_u24_e32 v3, 0x210, v146
	v_mov_b32_e32 v125, v121
	v_lshlrev_b32_e32 v5, 7, v146
	v_lshlrev_b32_e32 v2, 12, v197
	v_lshlrev_b32_e32 v6, 12, v109
	v_lshlrev_b32_e32 v8, 12, v111
	v_lshlrev_b32_e32 v10, 12, v113
	v_or_b32_e32 v48, v174, v146
	v_lshl_add_u64 v[12:13], s[64:65], 0, v[124:125]
	v_lshl_or_b32 v14, v252, 12, v5
	v_mov_b32_e32 v15, v121
	v_add3_u32 v187, v1, v124, 0
	v_add3_u32 v1, v3, v120, 0
	s_mov_b32 s13, 0
	v_cmp_eq_u32_e64 s[8:9], 0, v184
	v_cmp_gt_u32_e64 s[10:11], 2, v181
	v_or_b32_e32 v184, 31, v174
	v_or_b32_e32 v49, 16, v48
	v_lshl_add_u64 v[50:51], v[12:13], 0, v[14:15]
	v_lshl_add_u64 v[52:53], s[50:51], 0, v[120:121]
	v_mov_b32_e32 v54, v48
	v_mov_b32_e32 v55, v48
	v_add_u32_e32 v197, 0x9000, v1
	v_lshlrev_b32_e32 v56, 1, v112
	v_lshlrev_b32_e32 v58, 1, v0
	v_lshlrev_b32_e32 v60, 1, v108
	v_lshlrev_b32_e32 v62, 1, v110
	v_lshlrev_b32_e32 v120, 1, v114
	v_lshlrev_b32_e32 v64, 1, v2
	v_lshlrev_b32_e32 v66, 1, v4
	v_lshlrev_b32_e32 v68, 1, v6
	v_lshlrev_b32_e32 v70, 1, v8
	v_lshlrev_b32_e32 v72, 1, v10
	s_movk_i32 s4, 0x180
	s_mov_b32 s5, 0xf149f2ca
	s_mov_b32 s22, 0xefa18f08
	v_lshlrev_b32_e32 v74, 1, v122
	v_mov_b32_e32 v57, v121
	v_mov_b32_e32 v59, v121
	v_mov_b32_e32 v61, v121
	v_mov_b32_e32 v63, v121
	v_mov_b32_e32 v198, 0xf149f2ca
	s_mov_b32 s23, s2
	v_readfirstlane_b32 s90, v196
	s_nop 3
	s_cmp_ge_u32 s90, 4
	s_cbranch_scc0 .Lown_prio_done
	s_setprio 1
.Lown_prio_done:
	s_branch .LBB0_278
.LBB0_277:
	s_ashr_i32 s0, s23, 7
	s_ashr_i32 s1, s0, 31
	s_lshl_b64 s[0:1], s[0:1], 22
	s_waitcnt vmcnt(0)
	v_lshlrev_b32_e32 v20, 10, v140
	v_mov_b32_e32 v21, v121
	v_lshl_add_u64 v[20:21], s[0:1], 0, v[20:21]
	v_lshlrev_b64 v[20:21], 1, v[20:21]
	s_lshl_b32 s0, s14, 7
	v_lshl_add_u64 v[22:23], s[70:71], 0, v[20:21]
	s_and_b32 s12, s0, 0x380
	v_lshl_add_u64 v[22:23], v[22:23], 0, s[12:13]
	v_mov_b32_e32 v75, v121
	v_lshl_add_u64 v[140:141], v[22:23], 0, v[74:75]
	s_mov_b64 s[72:73], 0x8000
	global_load_dwordx2 v[234:235], v[140:141], off offset:1024
	global_load_dwordx2 v[236:237], v[140:141], off offset:1056
	global_load_dwordx2 v[238:239], v[140:141], off offset:1088
	global_load_dwordx2 v[240:241], v[140:141], off offset:1120
	v_lshl_add_u64 v[250:251], v[140:141], 0, s[72:73]
	global_load_dwordx2 v[242:243], v[250:251], off offset:1024
	global_load_dwordx2 v[244:245], v[250:251], off offset:1056
	global_load_dwordx2 v[246:247], v[250:251], off offset:1088
	global_load_dwordx2 v[248:249], v[250:251], off offset:1120
	v_max_f32_e32 v22, v132, v132
	v_max_f32_e32 v23, v71, v71
	s_waitcnt vmcnt(9)
	v_max_f32_e32 v30, v23, v22
	v_sub_f32_e32 v22, v71, v30
	v_sub_f32_e32 v23, v132, v30
	v_exp_f32_e32 v22, v22
	v_exp_f32_e32 v23, v23
	v_max_f32_e32 v24, v148, v148
	v_max_f32_e32 v24, v30, v24
	v_mov_b32_e32 v132, v114
	v_sub_f32_e32 v30, v30, v24
	v_exp_f32_e32 v139, v30
	v_pk_mul_f32 v[30:31], v[132:133], v[22:23]
	v_sub_f32_e32 v65, v148, v24
	v_pk_fma_f32 v[132:133], v[132:133], v[22:23], v[30:31] op_sel_hi:[1,1,0]
	v_lshlrev_b32_e32 v26, 16, v142
	v_exp_f32_e32 v132, v65
	v_and_b32_e32 v27, 0xffff0000, v142
	v_lshlrev_b32_e32 v28, 16, v143
	v_and_b32_e32 v29, 0xffff0000, v143
	v_max_f32_e32 v25, v152, v152
	s_waitcnt vmcnt(8)
	v_pk_mul_f32 v[32:33], v[30:31], v[26:27] op_sel:[1,0]
	v_max_f32_e32 v25, v24, v25
	v_mov_b32_e32 v26, v139
	v_pk_mul_f32 v[148:149], v[30:31], v[28:29] op_sel:[1,0]
	v_pk_fma_f32 v[32:33], v[44:45], v[22:23], v[32:33] op_sel_hi:[1,0,1]
	v_sub_f32_e32 v24, v24, v25
	v_pk_fma_f32 v[44:45], v[46:47], v[22:23], v[148:149] op_sel_hi:[1,0,1]
	v_pk_mul_f32 v[46:47], v[26:27], v[32:33] op_sel_hi:[0,1]
	v_pk_mul_f32 v[32:33], v[138:139], v[132:133]
	v_sub_f32_e32 v67, v152, v25
	v_exp_f32_e32 v137, v24
	v_pk_fma_f32 v[132:133], v[138:139], v[132:133], v[32:33] op_sel_hi:[1,1,0]
	v_lshlrev_b32_e32 v34, 16, v150
	v_exp_f32_e32 v132, v67
	v_and_b32_e32 v35, 0xffff0000, v150
	v_mov_b32_e32 v28, v137
	v_pk_fma_f32 v[34:35], v[32:33], v[34:35], v[46:47] op_sel_hi:[0,1,1]
	v_pk_mul_f32 v[138:139], v[28:29], v[34:35] op_sel_hi:[0,1]
	v_pk_mul_f32 v[34:35], v[136:137], v[132:133]
	v_lshlrev_b32_e32 v142, 16, v151
	v_and_b32_e32 v143, 0xffff0000, v151
	v_pk_mul_f32 v[44:45], v[26:27], v[44:45] op_sel_hi:[0,1]
	v_add_f32_e32 v23, v34, v35
	v_pk_fma_f32 v[46:47], v[32:33], v[142:143], v[44:45] op_sel_hi:[0,1,1]
	v_rcp_f32_e32 v44, v23
	v_lshlrev_b32_e32 v150, 16, v154
	v_and_b32_e32 v151, 0xffff0000, v154
	v_lshlrev_b32_e32 v154, 16, v155
	v_and_b32_e32 v155, 0xffff0000, v155
	v_pk_mul_f32 v[46:47], v[28:29], v[46:47] op_sel_hi:[0,1]
	v_pk_fma_f32 v[132:133], v[34:35], v[150:151], v[138:139] op_sel_hi:[0,1,1]
	v_pk_fma_f32 v[46:47], v[34:35], v[154:155], v[46:47] op_sel_hi:[0,1,1]
	v_pk_mul_f32 v[132:133], v[44:45], v[132:133] op_sel_hi:[0,1]
	v_pk_mul_f32 v[46:47], v[44:45], v[46:47] op_sel_hi:[0,1]
	v_readlane_b32 s16, v254, 2
	v_readlane_b32 s17, v254, 3
	s_add_i32 s23, s23, s3
	s_cmpk_lt_i32 s23, 0x800
	v_lshl_add_u64 v[24:25], s[16:17], 0, v[20:21]
	v_lshl_add_u64 v[24:25], v[24:25], 0, s[12:13]
	v_lshl_add_u64 v[24:25], v[24:25], 0, v[74:75]
	v_or_b32_e32 v20, 0x8000, v20
	v_readlane_b32 s18, v254, 4
	v_readlane_b32 s19, v254, 5
	s_waitcnt vmcnt(7)
	v_mov_b32_e32 v156, v234
	v_mov_b32_e32 v157, v235
	v_lshlrev_b32_e32 v136, 16, v156
	v_and_b32_e32 v137, 0xffff0000, v156
	v_lshlrev_b32_e32 v138, 16, v157
	v_and_b32_e32 v139, 0xffff0000, v157
	v_mul_f32_e32 v23, 0xbfb8aa3b, v136
	v_mul_f32_e32 v27, 0xbfb8aa3b, v137
	v_mul_f32_e32 v29, 0xbfb8aa3b, v138
	v_mul_f32_e32 v45, 0xbfb8aa3b, v139
	v_exp_f32_e32 v23, v23
	v_exp_f32_e32 v27, v27
	v_exp_f32_e32 v29, v29
	v_exp_f32_e32 v45, v45
	v_add_f32_e32 v23, 1.0, v23
	v_add_f32_e32 v27, 1.0, v27
	v_add_f32_e32 v29, 1.0, v29
	v_add_f32_e32 v45, 1.0, v45
	v_rcp_f32_e32 v142, v23
	v_rcp_f32_e32 v143, v27
	v_rcp_f32_e32 v148, v29
	v_rcp_f32_e32 v149, v45
	v_pk_mul_f32 v[132:133], v[132:133], v[136:137]
	v_pk_mul_f32 v[46:47], v[46:47], v[138:139]
	v_pk_mul_f32 v[132:133], v[132:133], v[142:143]
	v_pk_mul_f32 v[46:47], v[46:47], v[148:149]
	v_cvt_pk_bf16_f32 v132, v132, v133
	v_cvt_pk_bf16_f32 v133, v46, v47
	global_store_dwordx2 v[24:25], v[132:133], off offset:1024
	v_lshlrev_b32_e32 v132, 16, v128
	v_and_b32_e32 v133, 0xffff0000, v128
	v_lshlrev_b32_e32 v128, 16, v129
	v_and_b32_e32 v129, 0xffff0000, v129
	v_pk_mul_f32 v[132:133], v[30:31], v[132:133] op_sel:[1,0]
	v_pk_mul_f32 v[128:129], v[30:31], v[128:129] op_sel:[1,0]
	v_pk_fma_f32 v[40:41], v[40:41], v[22:23], v[132:133] op_sel_hi:[1,0,1]
	v_pk_fma_f32 v[42:43], v[42:43], v[22:23], v[128:129] op_sel_hi:[1,0,1]
	v_lshlrev_b32_e32 v136, 16, v130
	v_and_b32_e32 v137, 0xffff0000, v130
	v_lshlrev_b32_e32 v130, 16, v131
	v_and_b32_e32 v131, 0xffff0000, v131
	v_pk_mul_f32 v[40:41], v[26:27], v[40:41] op_sel_hi:[0,1]
	v_pk_mul_f32 v[42:43], v[26:27], v[42:43] op_sel_hi:[0,1]
	v_pk_fma_f32 v[40:41], v[32:33], v[136:137], v[40:41] op_sel_hi:[0,1,1]
	v_pk_fma_f32 v[42:43], v[32:33], v[130:131], v[42:43] op_sel_hi:[0,1,1]
	v_lshlrev_b32_e32 v138, 16, v134
	v_and_b32_e32 v139, 0xffff0000, v134
	v_lshlrev_b32_e32 v134, 16, v135
	v_and_b32_e32 v135, 0xffff0000, v135
	v_pk_mul_f32 v[40:41], v[28:29], v[40:41] op_sel_hi:[0,1]
	v_pk_mul_f32 v[42:43], v[28:29], v[42:43] op_sel_hi:[0,1]
	v_pk_fma_f32 v[40:41], v[34:35], v[138:139], v[40:41] op_sel_hi:[0,1,1]
	v_pk_fma_f32 v[42:43], v[34:35], v[134:135], v[42:43] op_sel_hi:[0,1,1]
	v_pk_mul_f32 v[40:41], v[44:45], v[40:41] op_sel_hi:[0,1]
	v_pk_mul_f32 v[42:43], v[44:45], v[42:43] op_sel_hi:[0,1]
	s_waitcnt vmcnt(7)
	v_mov_b32_e32 v46, v236
	v_mov_b32_e32 v47, v237
	v_lshlrev_b32_e32 v128, 16, v46
	v_and_b32_e32 v129, 0xffff0000, v46
	v_lshlrev_b32_e32 v46, 16, v47
	v_and_b32_e32 v47, 0xffff0000, v47
	v_mul_f32_e32 v23, 0xbfb8aa3b, v128
	v_mul_f32_e32 v27, 0xbfb8aa3b, v129
	v_mul_f32_e32 v29, 0xbfb8aa3b, v46
	v_mul_f32_e32 v45, 0xbfb8aa3b, v47
	v_exp_f32_e32 v23, v23
	v_exp_f32_e32 v27, v27
	v_exp_f32_e32 v29, v29
	v_exp_f32_e32 v45, v45
	v_add_f32_e32 v23, 1.0, v23
	v_add_f32_e32 v27, 1.0, v27
	v_add_f32_e32 v29, 1.0, v29
	v_add_f32_e32 v45, 1.0, v45
	v_rcp_f32_e32 v130, v23
	v_rcp_f32_e32 v131, v27
	v_rcp_f32_e32 v132, v29
	v_rcp_f32_e32 v133, v45
	v_pk_mul_f32 v[40:41], v[40:41], v[128:129]
	v_pk_mul_f32 v[42:43], v[42:43], v[46:47]
	v_pk_mul_f32 v[40:41], v[40:41], v[130:131]
	v_pk_mul_f32 v[42:43], v[42:43], v[132:133]
	v_cvt_pk_bf16_f32 v40, v40, v41
	v_cvt_pk_bf16_f32 v41, v42, v43
	global_store_dwordx2 v[24:25], v[40:41], off offset:1056
	v_lshlrev_b32_e32 v42, 16, v118
	v_and_b32_e32 v43, 0xffff0000, v118
	v_lshlrev_b32_e32 v46, 16, v119
	v_and_b32_e32 v47, 0xffff0000, v119
	v_pk_mul_f32 v[42:43], v[30:31], v[42:43] op_sel:[1,0]
	v_pk_mul_f32 v[46:47], v[30:31], v[46:47] op_sel:[1,0]
	v_pk_fma_f32 v[36:37], v[36:37], v[22:23], v[42:43] op_sel_hi:[1,0,1]
	v_pk_fma_f32 v[38:39], v[38:39], v[22:23], v[46:47] op_sel_hi:[1,0,1]
	v_lshlrev_b32_e32 v118, 16, v124
	v_and_b32_e32 v119, 0xffff0000, v124
	v_lshlrev_b32_e32 v124, 16, v125
	v_and_b32_e32 v125, 0xffff0000, v125
	v_pk_mul_f32 v[36:37], v[26:27], v[36:37] op_sel_hi:[0,1]
	v_pk_mul_f32 v[38:39], v[26:27], v[38:39] op_sel_hi:[0,1]
	v_pk_fma_f32 v[36:37], v[32:33], v[118:119], v[36:37] op_sel_hi:[0,1,1]
	v_pk_fma_f32 v[38:39], v[32:33], v[124:125], v[38:39] op_sel_hi:[0,1,1]
	v_lshlrev_b32_e32 v128, 16, v126
	v_and_b32_e32 v129, 0xffff0000, v126
	v_lshlrev_b32_e32 v126, 16, v127
	v_and_b32_e32 v127, 0xffff0000, v127
	v_pk_mul_f32 v[36:37], v[28:29], v[36:37] op_sel_hi:[0,1]
	v_pk_mul_f32 v[38:39], v[28:29], v[38:39] op_sel_hi:[0,1]
	v_pk_fma_f32 v[36:37], v[34:35], v[128:129], v[36:37] op_sel_hi:[0,1,1]
	v_pk_fma_f32 v[38:39], v[34:35], v[126:127], v[38:39] op_sel_hi:[0,1,1]
	v_pk_mul_f32 v[36:37], v[44:45], v[36:37] op_sel_hi:[0,1]
	v_pk_mul_f32 v[38:39], v[44:45], v[38:39] op_sel_hi:[0,1]
	s_waitcnt vmcnt(7)
	v_mov_b32_e32 v40, v238
	v_mov_b32_e32 v41, v239
	v_lshlrev_b32_e32 v42, 16, v40
	v_and_b32_e32 v43, 0xffff0000, v40
	v_lshlrev_b32_e32 v40, 16, v41
	v_and_b32_e32 v41, 0xffff0000, v41
	v_mul_f32_e32 v23, 0xbfb8aa3b, v42
	v_mul_f32_e32 v27, 0xbfb8aa3b, v43
	v_mul_f32_e32 v29, 0xbfb8aa3b, v40
	v_mul_f32_e32 v45, 0xbfb8aa3b, v41
	v_exp_f32_e32 v23, v23
	v_exp_f32_e32 v27, v27
	v_exp_f32_e32 v29, v29
	v_exp_f32_e32 v45, v45
	v_add_f32_e32 v23, 1.0, v23
	v_add_f32_e32 v27, 1.0, v27
	v_add_f32_e32 v29, 1.0, v29
	v_add_f32_e32 v45, 1.0, v45
	v_rcp_f32_e32 v46, v23
	v_rcp_f32_e32 v47, v27
	v_rcp_f32_e32 v118, v29
	v_rcp_f32_e32 v119, v45
	v_pk_mul_f32 v[36:37], v[36:37], v[42:43]
	v_pk_mul_f32 v[38:39], v[38:39], v[40:41]
	v_pk_mul_f32 v[36:37], v[36:37], v[46:47]
	v_pk_mul_f32 v[38:39], v[38:39], v[118:119]
	v_cvt_pk_bf16_f32 v36, v36, v37
	v_cvt_pk_bf16_f32 v37, v38, v39
	global_store_dwordx2 v[24:25], v[36:37], off offset:1088
	v_lshlrev_b32_e32 v38, 16, v112
	v_and_b32_e32 v39, 0xffff0000, v112
	v_lshlrev_b32_e32 v40, 16, v113
	v_and_b32_e32 v41, 0xffff0000, v113
	v_pk_mul_f32 v[38:39], v[30:31], v[38:39] op_sel:[1,0]
	v_pk_mul_f32 v[40:41], v[30:31], v[40:41] op_sel:[1,0]
	v_pk_fma_f32 v[16:17], v[16:17], v[22:23], v[38:39] op_sel_hi:[1,0,1]
	v_pk_fma_f32 v[18:19], v[18:19], v[22:23], v[40:41] op_sel_hi:[1,0,1]
	v_lshlrev_b32_e32 v42, 16, v110
	v_and_b32_e32 v43, 0xffff0000, v110
	v_lshlrev_b32_e32 v46, 16, v111
	v_and_b32_e32 v47, 0xffff0000, v111
	v_pk_mul_f32 v[16:17], v[26:27], v[16:17] op_sel_hi:[0,1]
	v_pk_mul_f32 v[18:19], v[26:27], v[18:19] op_sel_hi:[0,1]
	v_pk_fma_f32 v[16:17], v[32:33], v[42:43], v[16:17] op_sel_hi:[0,1,1]
	v_pk_fma_f32 v[18:19], v[32:33], v[46:47], v[18:19] op_sel_hi:[0,1,1]
	v_pk_mul_f32 v[16:17], v[28:29], v[16:17] op_sel_hi:[0,1]
	v_pk_mul_f32 v[18:19], v[28:29], v[18:19] op_sel_hi:[0,1]
	v_lshlrev_b32_e32 v110, 16, v116
	v_and_b32_e32 v111, 0xffff0000, v116
	v_lshlrev_b32_e32 v112, 16, v117
	v_and_b32_e32 v113, 0xffff0000, v117
	v_pk_fma_f32 v[16:17], v[34:35], v[110:111], v[16:17] op_sel_hi:[0,1,1]
	v_pk_fma_f32 v[18:19], v[34:35], v[112:113], v[18:19] op_sel_hi:[0,1,1]
	v_pk_mul_f32 v[16:17], v[44:45], v[16:17] op_sel_hi:[0,1]
	v_pk_mul_f32 v[18:19], v[44:45], v[18:19] op_sel_hi:[0,1]
	v_lshl_add_u64 v[116:117], s[70:71], 0, v[20:21]
	v_lshl_add_u64 v[116:117], v[116:117], 0, s[12:13]
	v_lshl_add_u64 v[30:31], v[116:117], 0, v[74:75]
	v_lshlrev_b32_e32 v34, 16, v108
	v_and_b32_e32 v35, 0xffff0000, v108
	s_waitcnt vmcnt(7)
	v_mov_b32_e32 v36, v240
	v_mov_b32_e32 v37, v241
	v_lshlrev_b32_e32 v22, 16, v36
	v_and_b32_e32 v23, 0xffff0000, v36
	v_lshlrev_b32_e32 v26, 16, v37
	v_and_b32_e32 v27, 0xffff0000, v37
	v_mul_f32_e32 v28, 0xbfb8aa3b, v22
	v_mul_f32_e32 v29, 0xbfb8aa3b, v23
	v_mul_f32_e32 v32, 0xbfb8aa3b, v26
	v_mul_f32_e32 v33, 0xbfb8aa3b, v27
	v_exp_f32_e32 v28, v28
	v_exp_f32_e32 v29, v29
	v_exp_f32_e32 v32, v32
	v_exp_f32_e32 v33, v33
	v_add_f32_e32 v28, 1.0, v28
	v_add_f32_e32 v29, 1.0, v29
	v_add_f32_e32 v32, 1.0, v32
	v_add_f32_e32 v33, 1.0, v33
	v_rcp_f32_e32 v28, v28
	v_rcp_f32_e32 v29, v29
	v_rcp_f32_e32 v32, v32
	v_rcp_f32_e32 v33, v33
	v_pk_mul_f32 v[16:17], v[16:17], v[22:23]
	v_pk_mul_f32 v[18:19], v[18:19], v[26:27]
	v_pk_mul_f32 v[16:17], v[16:17], v[28:29]
	v_pk_mul_f32 v[18:19], v[18:19], v[32:33]
	v_cvt_pk_bf16_f32 v16, v16, v17
	v_cvt_pk_bf16_f32 v17, v18, v19
	global_store_dwordx2 v[24:25], v[16:17], off offset:1120
	v_max_f32_e32 v16, v90, v90
	v_max_f32_e32 v17, v69, v69
	v_max_f32_e32 v38, v17, v16
	v_sub_f32_e32 v16, v69, v38
	v_sub_f32_e32 v17, v90, v38
	v_max_f32_e32 v22, v104, v104
	v_exp_f32_e32 v16, v16
	v_exp_f32_e32 v17, v17
	v_max_f32_e32 v23, v102, v102
	v_max_f32_e32 v22, v38, v22
	v_max_f32_e32 v23, v22, v23
	v_mov_b32_e32 v90, v115
	v_sub_f32_e32 v38, v38, v22
	v_sub_f32_e32 v44, v104, v22
	v_sub_f32_e32 v22, v22, v23
	v_sub_f32_e32 v45, v102, v23
	v_exp_f32_e32 v99, v22
	v_lshl_add_u64 v[22:23], s[16:17], 0, v[20:21]
	v_pk_mul_f32 v[20:21], v[90:91], v[16:17]
	v_exp_f32_e32 v95, v38
	v_pk_fma_f32 v[40:41], v[90:91], v[16:17], v[20:21] op_sel_hi:[1,1,0]
	v_lshlrev_b32_e32 v18, 16, v100
	v_exp_f32_e32 v40, v44
	v_and_b32_e32 v19, 0xffff0000, v100
	v_lshlrev_b32_e32 v24, 16, v101
	v_and_b32_e32 v25, 0xffff0000, v101
	v_lshl_add_u64 v[38:39], v[22:23], 0, s[12:13]
	v_pk_mul_f32 v[42:43], v[20:21], v[18:19] op_sel:[1,0]
	v_pk_mul_f32 v[24:25], v[20:21], v[24:25] op_sel:[1,0]
	v_mov_b32_e32 v22, v95
	v_lshl_add_u64 v[18:19], v[38:39], 0, v[74:75]
	v_pk_fma_f32 v[38:39], v[12:13], v[16:17], v[42:43] op_sel_hi:[1,0,1]
	v_pk_fma_f32 v[14:15], v[14:15], v[16:17], v[24:25] op_sel_hi:[1,0,1]
	v_pk_mul_f32 v[24:25], v[22:23], v[38:39] op_sel_hi:[0,1]
	v_pk_mul_f32 v[38:39], v[22:23], v[14:15] op_sel_hi:[0,1]
	v_pk_mul_f32 v[14:15], v[94:95], v[40:41]
	v_lshlrev_b32_e32 v26, 16, v106
	v_pk_fma_f32 v[40:41], v[94:95], v[40:41], v[14:15] op_sel_hi:[1,1,0]
	v_and_b32_e32 v27, 0xffff0000, v106
	v_exp_f32_e32 v40, v45
	v_lshlrev_b32_e32 v32, 16, v107
	v_and_b32_e32 v33, 0xffff0000, v107
	v_mov_b32_e32 v12, v99
	v_pk_fma_f32 v[24:25], v[14:15], v[26:27], v[24:25] op_sel_hi:[0,1,1]
	v_pk_fma_f32 v[32:33], v[14:15], v[32:33], v[38:39] op_sel_hi:[0,1,1]
	v_pk_mul_f32 v[38:39], v[12:13], v[24:25] op_sel_hi:[0,1]
	v_pk_mul_f32 v[24:25], v[98:99], v[40:41]
	v_lshlrev_b32_e32 v36, 16, v109
	v_add_f32_e32 v13, v24, v25
	v_rcp_f32_e32 v26, v13
	v_and_b32_e32 v37, 0xffff0000, v109
	v_pk_mul_f32 v[32:33], v[12:13], v[32:33] op_sel_hi:[0,1]
	v_pk_fma_f32 v[34:35], v[24:25], v[34:35], v[38:39] op_sel_hi:[0,1,1]
	v_pk_fma_f32 v[32:33], v[24:25], v[36:37], v[32:33] op_sel_hi:[0,1,1]
	v_pk_mul_f32 v[34:35], v[26:27], v[34:35] op_sel_hi:[0,1]
	v_pk_mul_f32 v[32:33], v[26:27], v[32:33] op_sel_hi:[0,1]
	v_lshlrev_b32_e32 v42, 16, v97
	v_and_b32_e32 v43, 0xffff0000, v97
	s_waitcnt vmcnt(7)
	v_mov_b32_e32 v28, v242
	v_mov_b32_e32 v29, v243
	v_lshlrev_b32_e32 v36, 16, v28
	v_and_b32_e32 v37, 0xffff0000, v28
	v_lshlrev_b32_e32 v28, 16, v29
	v_and_b32_e32 v29, 0xffff0000, v29
	v_mul_f32_e32 v13, 0xbfb8aa3b, v36
	v_mul_f32_e32 v17, 0xbfb8aa3b, v37
	v_mul_f32_e32 v23, 0xbfb8aa3b, v28
	v_mul_f32_e32 v27, 0xbfb8aa3b, v29
	v_exp_f32_e32 v13, v13
	v_exp_f32_e32 v17, v17
	v_exp_f32_e32 v23, v23
	v_exp_f32_e32 v27, v27
	v_add_f32_e32 v13, 1.0, v13
	v_add_f32_e32 v17, 1.0, v17
	v_add_f32_e32 v23, 1.0, v23
	v_add_f32_e32 v27, 1.0, v27
	v_rcp_f32_e32 v38, v13
	v_rcp_f32_e32 v39, v17
	v_rcp_f32_e32 v40, v23
	v_rcp_f32_e32 v41, v27
	v_pk_mul_f32 v[34:35], v[34:35], v[36:37]
	v_pk_mul_f32 v[28:29], v[32:33], v[28:29]
	v_pk_mul_f32 v[32:33], v[34:35], v[38:39]
	v_pk_mul_f32 v[28:29], v[28:29], v[40:41]
	v_cvt_pk_bf16_f32 v32, v32, v33
	v_cvt_pk_bf16_f32 v33, v28, v29
	global_store_dwordx2 v[18:19], v[32:33], off offset:1024
	v_lshlrev_b32_e32 v32, 16, v88
	v_and_b32_e32 v33, 0xffff0000, v88
	v_lshlrev_b32_e32 v34, 16, v89
	v_and_b32_e32 v35, 0xffff0000, v89
	v_pk_mul_f32 v[32:33], v[20:21], v[32:33] op_sel:[1,0]
	v_pk_mul_f32 v[34:35], v[20:21], v[34:35] op_sel:[1,0]
	v_pk_fma_f32 v[8:9], v[8:9], v[16:17], v[32:33] op_sel_hi:[1,0,1]
	v_pk_fma_f32 v[10:11], v[10:11], v[16:17], v[34:35] op_sel_hi:[1,0,1]
	v_lshlrev_b32_e32 v36, 16, v92
	v_and_b32_e32 v37, 0xffff0000, v92
	v_lshlrev_b32_e32 v38, 16, v93
	v_and_b32_e32 v39, 0xffff0000, v93
	v_pk_mul_f32 v[8:9], v[22:23], v[8:9] op_sel_hi:[0,1]
	v_pk_mul_f32 v[10:11], v[22:23], v[10:11] op_sel_hi:[0,1]
	v_pk_fma_f32 v[8:9], v[14:15], v[36:37], v[8:9] op_sel_hi:[0,1,1]
	v_pk_fma_f32 v[10:11], v[14:15], v[38:39], v[10:11] op_sel_hi:[0,1,1]
	v_lshlrev_b32_e32 v40, 16, v96
	v_and_b32_e32 v41, 0xffff0000, v96
	v_pk_mul_f32 v[8:9], v[12:13], v[8:9] op_sel_hi:[0,1]
	v_pk_mul_f32 v[10:11], v[12:13], v[10:11] op_sel_hi:[0,1]
	v_pk_fma_f32 v[8:9], v[24:25], v[40:41], v[8:9] op_sel_hi:[0,1,1]
	v_pk_fma_f32 v[10:11], v[24:25], v[42:43], v[10:11] op_sel_hi:[0,1,1]
	v_pk_mul_f32 v[8:9], v[26:27], v[8:9] op_sel_hi:[0,1]
	v_pk_mul_f32 v[10:11], v[26:27], v[10:11] op_sel_hi:[0,1]
	v_lshlrev_b32_e32 v38, 16, v87
	v_and_b32_e32 v39, 0xffff0000, v87
	s_waitcnt vmcnt(7)
	v_mov_b32_e32 v28, v244
	v_mov_b32_e32 v29, v245
	v_lshlrev_b32_e32 v32, 16, v28
	v_and_b32_e32 v33, 0xffff0000, v28
	v_lshlrev_b32_e32 v28, 16, v29
	v_and_b32_e32 v29, 0xffff0000, v29
	v_mul_f32_e32 v13, 0xbfb8aa3b, v32
	v_mul_f32_e32 v17, 0xbfb8aa3b, v33
	v_mul_f32_e32 v23, 0xbfb8aa3b, v28
	v_mul_f32_e32 v27, 0xbfb8aa3b, v29
	v_exp_f32_e32 v13, v13
	v_exp_f32_e32 v17, v17
	v_exp_f32_e32 v23, v23
	v_exp_f32_e32 v27, v27
	v_add_f32_e32 v13, 1.0, v13
	v_add_f32_e32 v17, 1.0, v17
	v_add_f32_e32 v23, 1.0, v23
	v_add_f32_e32 v27, 1.0, v27
	v_rcp_f32_e32 v34, v13
	v_rcp_f32_e32 v35, v17
	v_rcp_f32_e32 v36, v23
	v_rcp_f32_e32 v37, v27
	v_pk_mul_f32 v[8:9], v[8:9], v[32:33]
	v_pk_mul_f32 v[10:11], v[10:11], v[28:29]
	v_pk_mul_f32 v[8:9], v[8:9], v[34:35]
	v_pk_mul_f32 v[10:11], v[10:11], v[36:37]
	v_cvt_pk_bf16_f32 v8, v8, v9
	v_cvt_pk_bf16_f32 v9, v10, v11
	global_store_dwordx2 v[18:19], v[8:9], off offset:1056
	v_lshlrev_b32_e32 v10, 16, v82
	v_and_b32_e32 v11, 0xffff0000, v82
	v_lshlrev_b32_e32 v28, 16, v83
	v_and_b32_e32 v29, 0xffff0000, v83
	v_pk_mul_f32 v[10:11], v[20:21], v[10:11] op_sel:[1,0]
	v_pk_mul_f32 v[28:29], v[20:21], v[28:29] op_sel:[1,0]
	v_pk_fma_f32 v[4:5], v[4:5], v[16:17], v[10:11] op_sel_hi:[1,0,1]
	v_pk_fma_f32 v[6:7], v[6:7], v[16:17], v[28:29] op_sel_hi:[1,0,1]
	v_lshlrev_b32_e32 v32, 16, v84
	v_and_b32_e32 v33, 0xffff0000, v84
	v_lshlrev_b32_e32 v34, 16, v85
	v_and_b32_e32 v35, 0xffff0000, v85
	v_pk_mul_f32 v[4:5], v[22:23], v[4:5] op_sel_hi:[0,1]
	v_pk_mul_f32 v[6:7], v[22:23], v[6:7] op_sel_hi:[0,1]
	v_pk_fma_f32 v[4:5], v[14:15], v[32:33], v[4:5] op_sel_hi:[0,1,1]
	v_pk_fma_f32 v[6:7], v[14:15], v[34:35], v[6:7] op_sel_hi:[0,1,1]
	v_lshlrev_b32_e32 v36, 16, v86
	v_and_b32_e32 v37, 0xffff0000, v86
	v_pk_mul_f32 v[4:5], v[12:13], v[4:5] op_sel_hi:[0,1]
	v_pk_mul_f32 v[6:7], v[12:13], v[6:7] op_sel_hi:[0,1]
	v_pk_fma_f32 v[4:5], v[24:25], v[36:37], v[4:5] op_sel_hi:[0,1,1]
	v_pk_fma_f32 v[6:7], v[24:25], v[38:39], v[6:7] op_sel_hi:[0,1,1]
	v_pk_mul_f32 v[4:5], v[26:27], v[4:5] op_sel_hi:[0,1]
	v_pk_mul_f32 v[6:7], v[26:27], v[6:7] op_sel_hi:[0,1]
	s_waitcnt vmcnt(7)
	v_mov_b32_e32 v8, v246
	v_mov_b32_e32 v9, v247
	v_lshlrev_b32_e32 v10, 16, v8
	v_and_b32_e32 v11, 0xffff0000, v8
	v_lshlrev_b32_e32 v8, 16, v9
	v_and_b32_e32 v9, 0xffff0000, v9
	v_mul_f32_e32 v13, 0xbfb8aa3b, v10
	v_mul_f32_e32 v17, 0xbfb8aa3b, v11
	v_mul_f32_e32 v23, 0xbfb8aa3b, v8
	v_mul_f32_e32 v27, 0xbfb8aa3b, v9
	v_exp_f32_e32 v13, v13
	v_exp_f32_e32 v17, v17
	v_exp_f32_e32 v23, v23
	v_exp_f32_e32 v27, v27
	v_add_f32_e32 v13, 1.0, v13
	v_add_f32_e32 v17, 1.0, v17
	v_add_f32_e32 v23, 1.0, v23
	v_add_f32_e32 v27, 1.0, v27
	v_rcp_f32_e32 v28, v13
	v_rcp_f32_e32 v29, v17
	v_rcp_f32_e32 v32, v23
	v_rcp_f32_e32 v33, v27
	v_pk_mul_f32 v[4:5], v[4:5], v[10:11]
	v_pk_mul_f32 v[6:7], v[6:7], v[8:9]
	v_pk_mul_f32 v[4:5], v[4:5], v[28:29]
	v_pk_mul_f32 v[6:7], v[6:7], v[32:33]
	v_cvt_pk_bf16_f32 v4, v4, v5
	v_cvt_pk_bf16_f32 v5, v6, v7
	global_store_dwordx2 v[18:19], v[4:5], off offset:1088
	v_lshlrev_b32_e32 v6, 16, v76
	v_and_b32_e32 v7, 0xffff0000, v76
	v_pk_mul_f32 v[6:7], v[20:21], v[6:7] op_sel:[1,0]
	v_lshlrev_b32_e32 v8, 16, v77
	v_and_b32_e32 v9, 0xffff0000, v77
	v_pk_fma_f32 v[0:1], v[0:1], v[16:17], v[6:7] op_sel_hi:[1,0,1]
	v_lshlrev_b32_e32 v10, 16, v80
	v_and_b32_e32 v11, 0xffff0000, v80
	v_pk_mul_f32 v[8:9], v[20:21], v[8:9] op_sel:[1,0]
	v_pk_mul_f32 v[0:1], v[22:23], v[0:1] op_sel_hi:[0,1]
	v_pk_fma_f32 v[2:3], v[2:3], v[16:17], v[8:9] op_sel_hi:[1,0,1]
	v_pk_fma_f32 v[0:1], v[14:15], v[10:11], v[0:1] op_sel_hi:[0,1,1]
	v_lshlrev_b32_e32 v28, 16, v81
	v_and_b32_e32 v29, 0xffff0000, v81
	v_pk_mul_f32 v[2:3], v[22:23], v[2:3] op_sel_hi:[0,1]
	v_pk_fma_f32 v[2:3], v[14:15], v[28:29], v[2:3] op_sel_hi:[0,1,1]
	v_lshlrev_b32_e32 v30, 16, v78
	v_and_b32_e32 v31, 0xffff0000, v78
	v_lshlrev_b32_e32 v32, 16, v79
	v_and_b32_e32 v33, 0xffff0000, v79
	v_pk_mul_f32 v[0:1], v[12:13], v[0:1] op_sel_hi:[0,1]
	v_pk_mul_f32 v[2:3], v[12:13], v[2:3] op_sel_hi:[0,1]
	v_pk_fma_f32 v[0:1], v[24:25], v[30:31], v[0:1] op_sel_hi:[0,1,1]
	v_pk_fma_f32 v[2:3], v[24:25], v[32:33], v[2:3] op_sel_hi:[0,1,1]
	v_pk_mul_f32 v[0:1], v[26:27], v[0:1] op_sel_hi:[0,1]
	v_pk_mul_f32 v[2:3], v[26:27], v[2:3] op_sel_hi:[0,1]
	s_waitcnt vmcnt(7)
	v_mov_b32_e32 v4, v248
	v_mov_b32_e32 v5, v249
	v_lshlrev_b32_e32 v6, 16, v4
	v_and_b32_e32 v7, 0xffff0000, v4
	v_lshlrev_b32_e32 v4, 16, v5
	v_and_b32_e32 v5, 0xffff0000, v5
	v_mul_f32_e32 v8, 0xbfb8aa3b, v6
	v_mul_f32_e32 v9, 0xbfb8aa3b, v7
	v_mul_f32_e32 v10, 0xbfb8aa3b, v4
	v_mul_f32_e32 v11, 0xbfb8aa3b, v5
	v_exp_f32_e32 v8, v8
	v_exp_f32_e32 v9, v9
	v_exp_f32_e32 v10, v10
	v_exp_f32_e32 v11, v11
	v_add_f32_e32 v8, 1.0, v8
	v_add_f32_e32 v9, 1.0, v9
	v_add_f32_e32 v10, 1.0, v10
	v_add_f32_e32 v11, 1.0, v11
	v_rcp_f32_e32 v8, v8
	v_rcp_f32_e32 v9, v9
	v_rcp_f32_e32 v10, v10
	v_rcp_f32_e32 v11, v11
	v_pk_mul_f32 v[0:1], v[0:1], v[6:7]
	v_pk_mul_f32 v[2:3], v[2:3], v[4:5]
	v_pk_mul_f32 v[0:1], v[0:1], v[8:9]
	v_pk_mul_f32 v[2:3], v[2:3], v[10:11]
	v_cvt_pk_bf16_f32 v0, v0, v1
	v_cvt_pk_bf16_f32 v1, v2, v3
	global_store_dwordx2 v[18:19], v[0:1], off offset:1120
	s_cbranch_scc0 .LBB0_298
